# v79: + work-queue ticket prefetch at the end of each unit's key loop
# baseline (speedup 1.0000x reference)
; #define LAS __attribute__((address_space(3)))
; __device__ __forceinline__ void attn_phase(const Params& P, LAS unsigned char* lds) {
;     int tid_ = threadIdx.x; asm volatile("" : "+v"(tid_)); const int tid = tid_;
;     unsigned* ctr = (unsigned*)(P.ws + WS_CTL);
;     LAS int* misc = (LAS int*)(lds + AL_MISC);
;     const int xq = (int)(__builtin_amdgcn_s_getreg((3 << 11) | 20) & 7u);
;     const bool bounded = ((const float*)(P.ws + WS_TAB))[TAB_DBOUND] <= 60.0f;
;     for (;;) {
;         if (tid == 0) { int u = -1;
;             for (int k = 0; k < 8; ++k) { const int qi = (xq + k) & 7; const unsigned v = atomicAdd(ctr + qi, 1u); if (v < (unsigned)QN) { u = qi * QN + (int)v; break; } }
;             misc[0] = u; }
.LBB0_418:
	v_writelane_b32 v255, s88, 3
	s_nop 1
	v_writelane_b32 v255, s89, 4
	v_writelane_b32 v255, s94, 5
	s_nop 1
	v_writelane_b32 v255, s95, 6
	s_or_b64 exec, exec, s[4:5]
	s_waitcnt lgkmcnt(0)
	v_mov_b32_e32 v0, v178
	v_mov_b32_e32 v1, 0x2000
	s_barrier
	s_getreg_b32 s3, hwreg(HW_REG_XCC_ID, 0, 4)
	global_load_dword v2, v1, s[52:53] offset:136
	global_load_dword v3, v1, s[52:53] offset:132
	s_lshr_b32 s72, s75, 16
	s_and_b32 s0, s75, 0xffff
	s_add_u32 s78, s52, 0x18324000
	s_addc_u32 s79, s53, 0
	s_add_u32 s80, s52, 0x1c324000
	s_addc_u32 s81, s53, 0
	s_add_u32 s82, s52, 0x124000
	s_addc_u32 s83, s53, 0
	s_add_u32 s60, s52, 0x2084
	s_addc_u32 s61, s53, 0
	s_add_u32 s84, s52, 0x20324000
	s_addc_u32 s85, s53, 0
	s_add_u32 s86, s52, 0x24324000
	s_addc_u32 s87, s53, 0
	s_add_u32 s88, s52, 0x28324000
	s_addc_u32 s89, s53, 0
	s_add_u32 s90, s52, 0x2c324000
	s_addc_u32 s91, s53, 0
	s_add_u32 s92, s52, 0x30324000
	s_addc_u32 s93, s53, 0
	s_mov_b32 s6, 0x22000
	s_add_u32 s62, s52, 0x2080
	s_mov_b32 s1, 0x42700000
	s_addc_u32 s63, s53, 0
	s_add_i32 s95, s6, 0x100
	s_mov_b32 s13, 0
	v_mov_b32_e32 v1, 0
	s_mov_b64 s[28:29], 0x2000
	s_movk_i32 s73, 0x4000
	s_movk_i32 s75, 0x81
	s_mov_b32 s76, 0x22100
	s_mov_b64 s[30:31], 0x4000
	s_mov_b64 s[36:37], 0x6000
	s_mov_b64 s[42:43], 0x28330000
	s_mov_b64 s[44:45], 0x28332000
	s_mov_b64 s[48:49], 0x2c330000
	s_mov_b64 s[50:51], 0x2c332000
	v_mov_b32_e32 v230, 0x358637bd
	v_mbcnt_hi_u32_b32 v179, -1, v173
	v_mov_b32_e32 v231, 0xff800000
	v_mov_b32_e32 v232, 0x100
	v_mad_u32_u24 v233, v172, s0, v254
	v_cmp_eq_u32_e64 s[4:5], 0, v0
	s_lshl_b32 s94, s0, 8
	v_mov_b32_e32 v234, s95
	v_mov_b32_e32 v235, 0x80
	s_and_saveexec_b64 s[64:65], s[4:5]
	s_cbranch_execz .Lqp_p
	s_and_b32 vcc_lo, s3, 7
	s_lshl_b32 vcc_lo, vcc_lo, 2
	v_mov_b32_e32 v4, vcc_lo
	v_mov_b32_e32 v5, 1
	global_atomic_add v253, v4, v5, s[52:53] sc0
.Lqp_p:
	s_or_b64 exec, exec, s[64:65]
	s_waitcnt vmcnt(0)
	v_cmp_ge_f32_e64 s[6:7], s1, v2
	v_mov_b32_e32 v4, 0x42f00000
	v_cmp_ge_f32_e64 s[100:101], v4, v3
	v_readfirstlane_b32 s0, v3
	s_nop 3
	v_writelane_b32 v255, s0, 8
	s_branch .LBB0_421

; __device__ __forceinline__ void attn_phase(const Params& P, LAS unsigned char* lds) {
;     ...
;         if (tid == 0) { int u = -1;
;             for (int k = 0; k < 8; ++k) { const int qi = (xq + k) & 7; const unsigned v = atomicAdd(ctr + qi, 1u); if (v < (unsigned)QN) { u = qi * QN + (int)v; break; } }
;             misc[0] = u; }
;         __syncthreads();
;         const int u = misc[0];
;         __syncthreads();
;         if (u < 0) break;
.LBB0_420:
.LBB0_421:
	s_and_saveexec_b64 s[64:65], s[4:5]
	s_cbranch_execz .LBB0_427
	s_and_b32 s1, s3, 7
	s_mulk_i32 s1, 0x180
	s_movk_i32 s8, 0x180
	v_cmp_gt_u32_e32 vcc, s8, v253
	v_add_u32_e32 v3, s1, v253
	v_mov_b32_e32 v0, -1
	s_mov_b64 s[66:67], 0
	s_mov_b32 s0, 1
	s_cbranch_vccz .LBB0_424
	v_mov_b32_e32 v0, v3
	s_branch .LBB0_426

; __device__ __forceinline__ float silu_f(float z) { return z * __builtin_amdgcn_rcpf(1.0f + __builtin_amdgcn_exp2f(-LOG2E * z)); }
; __device__ __forceinline__ float bf_lo(unsigned v) { return __uint_as_float(v << 16); }
; __device__ __forceinline__ float bf_hi(unsigned v) { return __uint_as_float(v & 0xffff0000u); }
; template <int MODE>
; __device__ __forceinline__ void attn_unit(const Params& P, LAS unsigned char* lds, const int b, const int h, const int qb) {
;     ...
;     bf16_t* mix = (bf16_t*)(P.ws + WS_MIX) + (tokbase + q) * DM + colO;
;     const bf16_t* zp = Zb + (size_t)q * RS;
;     const float inv1 = 1.0f / (l1 + __shfl_xor(l1, 32));
;     u32x2 zv[4][4]; f32x4 gv[4][4];
;     if (FOX || mp == 0) {
; #pragma unroll
;         for (int d = 0; d < 4; ++d)
; #pragma unroll
;             for (int a = 0; a < 4; ++a) { const int d0 = 32 * d + 8 * a + 4 * hh; zv[d][a] = *(const u32x2*)(zp + d0); if (!FOX) gv[d][a] = *(const f32x4*)(P.in[I_DON] + d0); }
;     }
;     asm volatile("" ::: "memory");
;     if (FOX) {
; #pragma unroll
;         for (int d = 0; d < 4; ++d)
; #pragma unroll
;             for (int a = 0; a < 4; ++a) { const int d0 = 32 * d + 8 * a + 4 * hh; const u32x2 z2 = zv[d][a];
;                 const float o0 = O[d][4 * a] * inv1 * silu_f(bf_lo(z2.x)), o1 = O[d][4 * a + 1] * inv1 * silu_f(bf_hi(z2.x));
;                 const float o2 = O[d][4 * a + 2] * inv1 * silu_f(bf_lo(z2.y)), o3 = O[d][4 * a + 3] * inv1 * silu_f(bf_hi(z2.y));
;                 u32x2 ov; ov.x = cvt_pk_bf16(o0, o1); ov.y = cvt_pk_bf16(o2, o3); *(u32x2*)(mix + d0) = ov; }
.LBB0_465:
	s_and_saveexec_b64 s[8:9], s[4:5]
	s_cbranch_execz .Lqp_m0
	s_and_b32 vcc_lo, s3, 7
	s_lshl_b32 vcc_lo, vcc_lo, 2
	v_mov_b32_e32 v4, vcc_lo
	v_mov_b32_e32 v5, 1
	global_atomic_add v253, v4, v5, s[52:53] sc0
.Lqp_m0:
	s_or_b64 exec, exec, s[8:9]
	s_lshr_b32 s0, s12, 3
	s_add_u32 s8, s84, s64
	s_addc_u32 s9, s85, s65
	v_lshl_add_u64 v[2:3], v[182:183], 1, s[8:9]
	v_mov_b32_e32 v97, v1
	v_lshl_add_u64 v[2:3], v[2:3], 0, v[96:97]
	global_load_dwordx2 v[94:95], v[2:3], off
	global_load_dwordx2 v[98:99], v[2:3], off offset:16
	v_and_b32_e32 v6, 64, v179
	v_xor_b32_e32 v0, 32, v179
	v_add_u32_e32 v6, 64, v6
	v_cmp_lt_i32_e32 vcc, v0, v6
	global_load_dwordx2 v[100:101], v[2:3], off offset:32
	global_load_dwordx2 v[92:93], v[2:3], off offset:48
	global_load_dwordx2 v[90:91], v[2:3], off offset:64
	global_load_dwordx2 v[88:89], v[2:3], off offset:80
	global_load_dwordx2 v[86:87], v[2:3], off offset:96
	global_load_dwordx2 v[84:85], v[2:3], off offset:112
	global_load_dwordx2 v[82:83], v[2:3], off offset:128
	global_load_dwordx2 v[80:81], v[2:3], off offset:144
	global_load_dwordx2 v[14:15], v[2:3], off offset:160
	global_load_dwordx2 v[12:13], v[2:3], off offset:176
	global_load_dwordx2 v[10:11], v[2:3], off offset:192
	global_load_dwordx2 v[8:9], v[2:3], off offset:208
	global_load_dwordx2 v[6:7], v[2:3], off offset:224
	s_nop 0
	global_load_dwordx2 v[2:3], v[2:3], off offset:240
	v_cndmask_b32_e32 v0, v179, v0, vcc
	v_lshlrev_b32_e32 v0, 2, v0
	ds_bpermute_b32 v0, v0, v191
	s_mov_b32 s1, s13
	s_lshl_b64 s[0:1], s[0:1], 25
	s_add_u32 s0, s20, s0
	v_lshlrev_b64 v[4:5], 12, v[180:181]
	s_addc_u32 s1, s21, s1
	s_waitcnt lgkmcnt(0)
	v_add_f32_e32 v0, v191, v0
	v_lshl_add_u64 v[4:5], s[0:1], 0, v[4:5]
	v_div_scale_f32 v102, s[0:1], v0, v0, 1.0
	v_rcp_f32_e32 v103, v102
	s_lshl_b32 s8, s12, 8
	s_and_b32 s12, s8, 0x700
	v_lshl_add_u64 v[4:5], v[4:5], 0, s[12:13]
	v_lshl_add_u64 v[4:5], v[4:5], 0, v[96:97]
	v_fma_f32 v97, -v102, v103, 1.0
	v_div_scale_f32 v96, vcc, 1.0, v0, 1.0
	v_fmac_f32_e32 v103, v97, v103
	v_mul_f32_e32 v97, v96, v103
	v_fma_f32 v104, -v102, v97, v96
	v_fmac_f32_e32 v97, v104, v103
	v_fma_f32 v96, -v102, v97, v96
	v_div_fmas_f32 v96, v96, v103, v97
	v_div_fixup_f32 v0, v96, v0, 1.0
	v_pk_mul_f32 v[64:65], v[64:65], v[0:1] op_sel_hi:[1,0]
	v_pk_mul_f32 v[66:67], v[66:67], v[0:1] op_sel_hi:[1,0]
	v_pk_mul_f32 v[68:69], v[68:69], v[0:1] op_sel_hi:[1,0]
	v_pk_mul_f32 v[48:49], v[48:49], v[0:1] op_sel_hi:[1,0]
	v_pk_mul_f32 v[50:51], v[50:51], v[0:1] op_sel_hi:[1,0]
	v_pk_mul_f32 v[52:53], v[52:53], v[0:1] op_sel_hi:[1,0]
	v_pk_mul_f32 v[32:33], v[32:33], v[0:1] op_sel_hi:[1,0]
	v_pk_mul_f32 v[34:35], v[34:35], v[0:1] op_sel_hi:[1,0]
	v_pk_mul_f32 v[36:37], v[36:37], v[0:1] op_sel_hi:[1,0]
	s_mov_b64 s[8:9], 0
	s_waitcnt vmcnt(0)
	v_lshlrev_b32_e32 v96, 16, v94
	v_and_b32_e32 v97, 0xffff0000, v94
	v_lshlrev_b32_e32 v94, 16, v95
	v_and_b32_e32 v95, 0xffff0000, v95
	v_mul_f32_e32 v104, 0xbfb8aa3b, v96
	v_mul_f32_e32 v105, 0xbfb8aa3b, v97
	v_mul_f32_e32 v106, 0xbfb8aa3b, v94
	v_mul_f32_e32 v107, 0xbfb8aa3b, v95
	v_exp_f32_e32 v104, v104
	v_exp_f32_e32 v105, v105
	v_exp_f32_e32 v106, v106
	v_exp_f32_e32 v107, v107
	v_add_f32_e32 v104, 1.0, v104
	v_add_f32_e32 v105, 1.0, v105
	v_add_f32_e32 v106, 1.0, v106
	v_add_f32_e32 v107, 1.0, v107
	v_lshlrev_b32_e32 v102, 16, v98
	v_and_b32_e32 v103, 0xffff0000, v98
	v_rcp_f32_e32 v104, v104
	v_rcp_f32_e32 v105, v105
	v_rcp_f32_e32 v106, v106
	v_rcp_f32_e32 v107, v107
	v_lshlrev_b32_e32 v98, 16, v99
	v_and_b32_e32 v99, 0xffff0000, v99
	v_mul_f32_e32 v108, 0xbfb8aa3b, v102
	v_mul_f32_e32 v109, 0xbfb8aa3b, v103
	v_mul_f32_e32 v110, 0xbfb8aa3b, v98
	v_mul_f32_e32 v111, 0xbfb8aa3b, v99
	v_exp_f32_e32 v108, v108
	v_exp_f32_e32 v109, v109
	v_exp_f32_e32 v110, v110
	v_exp_f32_e32 v111, v111
	v_pk_mul_f32 v[96:97], v[104:105], v[96:97]
	v_pk_mul_f32 v[94:95], v[106:107], v[94:95]
	v_pk_mul_f32 v[64:65], v[64:65], v[96:97]
	v_pk_mul_f32 v[66:67], v[66:67], v[94:95]
	v_add_f32_e32 v108, 1.0, v108
	v_add_f32_e32 v109, 1.0, v109
	v_cvt_pk_bf16_f32 v64, v64, v65
	v_cvt_pk_bf16_f32 v65, v66, v67
	v_rcp_f32_e32 v108, v108
	global_store_dwordx2 v[4:5], v[64:65], off
	v_rcp_f32_e32 v109, v109
	v_add_f32_e32 v64, 1.0, v110
	v_add_f32_e32 v65, 1.0, v111
	v_rcp_f32_e32 v64, v64
	v_rcp_f32_e32 v65, v65
	v_pk_mul_f32 v[66:67], v[108:109], v[102:103]
	v_pk_mul_f32 v[64:65], v[64:65], v[98:99]
	v_pk_mul_f32 v[66:67], v[68:69], v[66:67]
	v_pk_mul_f32 v[68:69], v[70:71], v[0:1] op_sel_hi:[1,0]
	v_cvt_pk_bf16_f32 v66, v66, v67
	v_pk_mul_f32 v[64:65], v[68:69], v[64:65]
	v_lshlrev_b32_e32 v70, 16, v101
	v_cvt_pk_bf16_f32 v67, v64, v65
	v_lshlrev_b32_e32 v64, 16, v100
	v_mul_f32_e32 v65, 0xbfb8aa3b, v64
	global_store_dwordx2 v[4:5], v[66:67], off offset:16
	v_exp_f32_e32 v66, v65
	v_and_b32_e32 v65, 0xffff0000, v100
	v_mul_f32_e32 v67, 0xbfb8aa3b, v65
	v_and_b32_e32 v71, 0xffff0000, v101
	v_exp_f32_e32 v67, v67
	v_pk_mul_f32 v[68:69], v[72:73], v[0:1] op_sel_hi:[1,0]
	v_mul_f32_e32 v72, 0xbfb8aa3b, v70
	v_mul_f32_e32 v73, 0xbfb8aa3b, v71
	v_exp_f32_e32 v72, v72
	v_exp_f32_e32 v73, v73
	v_add_f32_e32 v66, 1.0, v66
	v_add_f32_e32 v67, 1.0, v67
	v_rcp_f32_e32 v66, v66
	v_rcp_f32_e32 v67, v67
	v_add_f32_e32 v72, 1.0, v72
	v_add_f32_e32 v73, 1.0, v73
	v_rcp_f32_e32 v72, v72
	v_rcp_f32_e32 v73, v73
	v_pk_mul_f32 v[64:65], v[66:67], v[64:65]
	v_pk_mul_f32 v[66:67], v[74:75], v[0:1] op_sel_hi:[1,0]
	v_pk_mul_f32 v[64:65], v[68:69], v[64:65]
	v_pk_mul_f32 v[68:69], v[72:73], v[70:71]
	v_cvt_pk_bf16_f32 v64, v64, v65
	v_pk_mul_f32 v[66:67], v[66:67], v[68:69]
	v_lshlrev_b32_e32 v70, 16, v93
	v_cvt_pk_bf16_f32 v65, v66, v67
; __device__ __forceinline__ float silu_f(float z) { return z * __builtin_amdgcn_rcpf(1.0f + __builtin_amdgcn_exp2f(-LOG2E * z)); }
; __device__ __forceinline__ float bf_lo(unsigned v) { return __uint_as_float(v << 16); }
; __device__ __forceinline__ float bf_hi(unsigned v) { return __uint_as_float(v & 0xffff0000u); }
; template <int MODE>
; __device__ __forceinline__ void attn_unit(const Params& P, LAS unsigned char* lds, const int b, const int h, const int qb) {
;     ...
;     if (FOX) {
; #pragma unroll
;         for (int d = 0; d < 4; ++d)
; #pragma unroll
;             for (int a = 0; a < 4; ++a) { const int d0 = 32 * d + 8 * a + 4 * hh; const u32x2 z2 = zv[d][a];
;                 const float o0 = O[d][4 * a] * inv1 * silu_f(bf_lo(z2.x)), o1 = O[d][4 * a + 1] * inv1 * silu_f(bf_hi(z2.x));
;                 const float o2 = O[d][4 * a + 2] * inv1 * silu_f(bf_lo(z2.y)), o3 = O[d][4 * a + 3] * inv1 * silu_f(bf_hi(z2.y));
;                 u32x2 ov; ov.x = cvt_pk_bf16(o0, o1); ov.y = cvt_pk_bf16(o2, o3); *(u32x2*)(mix + d0) = ov; }
	global_store_dwordx2 v[4:5], v[64:65], off offset:32
	v_lshlrev_b32_e32 v64, 16, v92
	v_mul_f32_e32 v65, 0xbfb8aa3b, v64
	v_exp_f32_e32 v66, v65
	v_and_b32_e32 v65, 0xffff0000, v92
	v_mul_f32_e32 v67, 0xbfb8aa3b, v65
	v_and_b32_e32 v71, 0xffff0000, v93
	v_exp_f32_e32 v67, v67
	v_mul_f32_e32 v72, 0xbfb8aa3b, v70
	v_mul_f32_e32 v73, 0xbfb8aa3b, v71
	v_exp_f32_e32 v72, v72
	v_exp_f32_e32 v73, v73
	v_add_f32_e32 v66, 1.0, v66
	v_add_f32_e32 v67, 1.0, v67
	v_rcp_f32_e32 v66, v66
	v_rcp_f32_e32 v67, v67
	v_add_f32_e32 v72, 1.0, v72
	v_add_f32_e32 v73, 1.0, v73
	v_rcp_f32_e32 v72, v72
	v_rcp_f32_e32 v73, v73
	v_pk_mul_f32 v[68:69], v[76:77], v[0:1] op_sel_hi:[1,0]
	v_pk_mul_f32 v[64:65], v[66:67], v[64:65]
	v_pk_mul_f32 v[66:67], v[78:79], v[0:1] op_sel_hi:[1,0]
	v_pk_mul_f32 v[64:65], v[68:69], v[64:65]
	v_pk_mul_f32 v[68:69], v[72:73], v[70:71]
	v_cvt_pk_bf16_f32 v64, v64, v65
	v_pk_mul_f32 v[66:67], v[66:67], v[68:69]
	v_lshlrev_b32_e32 v68, 16, v91
	v_cvt_pk_bf16_f32 v65, v66, v67
	global_store_dwordx2 v[4:5], v[64:65], off offset:48
	v_lshlrev_b32_e32 v64, 16, v90
	v_mul_f32_e32 v65, 0xbfb8aa3b, v64
	v_exp_f32_e32 v66, v65
	v_and_b32_e32 v65, 0xffff0000, v90
	v_mul_f32_e32 v67, 0xbfb8aa3b, v65
	v_and_b32_e32 v69, 0xffff0000, v91
	v_exp_f32_e32 v67, v67
	v_mul_f32_e32 v70, 0xbfb8aa3b, v68
	v_mul_f32_e32 v71, 0xbfb8aa3b, v69
	v_exp_f32_e32 v70, v70
	v_exp_f32_e32 v71, v71
	v_add_f32_e32 v66, 1.0, v66
	v_add_f32_e32 v67, 1.0, v67
	v_rcp_f32_e32 v66, v66
	v_rcp_f32_e32 v67, v67
	v_add_f32_e32 v70, 1.0, v70
	v_add_f32_e32 v71, 1.0, v71
	v_rcp_f32_e32 v70, v70
	v_rcp_f32_e32 v71, v71
	v_pk_mul_f32 v[64:65], v[66:67], v[64:65]
	s_nop 0
	v_pk_mul_f32 v[48:49], v[48:49], v[64:65]
	v_pk_mul_f32 v[64:65], v[70:71], v[68:69]
	v_cvt_pk_bf16_f32 v48, v48, v49
	v_pk_mul_f32 v[50:51], v[50:51], v[64:65]
	v_lshlrev_b32_e32 v64, 16, v89
	v_cvt_pk_bf16_f32 v49, v50, v51
	global_store_dwordx2 v[4:5], v[48:49], off offset:64
	v_lshlrev_b32_e32 v48, 16, v88
	v_mul_f32_e32 v49, 0xbfb8aa3b, v48
	v_exp_f32_e32 v50, v49
	v_and_b32_e32 v49, 0xffff0000, v88
	v_mul_f32_e32 v51, 0xbfb8aa3b, v49
	v_and_b32_e32 v65, 0xffff0000, v89
	v_exp_f32_e32 v51, v51
	v_mul_f32_e32 v66, 0xbfb8aa3b, v64
	v_mul_f32_e32 v67, 0xbfb8aa3b, v65
	v_exp_f32_e32 v66, v66
	v_exp_f32_e32 v67, v67
	v_add_f32_e32 v50, 1.0, v50
	v_add_f32_e32 v51, 1.0, v51
	v_rcp_f32_e32 v50, v50
	v_rcp_f32_e32 v51, v51
	v_add_f32_e32 v66, 1.0, v66
	v_add_f32_e32 v67, 1.0, v67
	v_rcp_f32_e32 v66, v66
	v_rcp_f32_e32 v67, v67
	v_pk_mul_f32 v[48:49], v[50:51], v[48:49]
	v_pk_mul_f32 v[50:51], v[54:55], v[0:1] op_sel_hi:[1,0]
	v_pk_mul_f32 v[48:49], v[52:53], v[48:49]
	v_pk_mul_f32 v[52:53], v[66:67], v[64:65]
	v_cvt_pk_bf16_f32 v48, v48, v49
	v_pk_mul_f32 v[50:51], v[50:51], v[52:53]
	v_lshlrev_b32_e32 v54, 16, v87
	v_cvt_pk_bf16_f32 v49, v50, v51
	global_store_dwordx2 v[4:5], v[48:49], off offset:80
	v_lshlrev_b32_e32 v48, 16, v86
	v_mul_f32_e32 v49, 0xbfb8aa3b, v48
	v_exp_f32_e32 v50, v49
	v_and_b32_e32 v49, 0xffff0000, v86
	v_mul_f32_e32 v51, 0xbfb8aa3b, v49
	v_and_b32_e32 v55, 0xffff0000, v87
	v_exp_f32_e32 v51, v51
	v_pk_mul_f32 v[52:53], v[56:57], v[0:1] op_sel_hi:[1,0]
	v_mul_f32_e32 v56, 0xbfb8aa3b, v54
	v_mul_f32_e32 v57, 0xbfb8aa3b, v55
	v_exp_f32_e32 v56, v56
	v_exp_f32_e32 v57, v57
	v_add_f32_e32 v50, 1.0, v50
	v_add_f32_e32 v51, 1.0, v51
	v_rcp_f32_e32 v50, v50
	v_rcp_f32_e32 v51, v51
	v_add_f32_e32 v56, 1.0, v56
	v_add_f32_e32 v57, 1.0, v57
	v_rcp_f32_e32 v56, v56
	v_rcp_f32_e32 v57, v57
	v_pk_mul_f32 v[48:49], v[50:51], v[48:49]
	v_pk_mul_f32 v[50:51], v[58:59], v[0:1] op_sel_hi:[1,0]
	v_pk_mul_f32 v[48:49], v[52:53], v[48:49]
	v_pk_mul_f32 v[52:53], v[56:57], v[54:55]
	v_cvt_pk_bf16_f32 v48, v48, v49
	v_pk_mul_f32 v[50:51], v[50:51], v[52:53]
	v_lshlrev_b32_e32 v54, 16, v85
	v_cvt_pk_bf16_f32 v49, v50, v51
	global_store_dwordx2 v[4:5], v[48:49], off offset:96
	v_lshlrev_b32_e32 v48, 16, v84
	v_mul_f32_e32 v49, 0xbfb8aa3b, v48
	v_exp_f32_e32 v50, v49
	v_and_b32_e32 v49, 0xffff0000, v84
	v_mul_f32_e32 v51, 0xbfb8aa3b, v49
	v_and_b32_e32 v55, 0xffff0000, v85
	v_exp_f32_e32 v51, v51
	v_mul_f32_e32 v56, 0xbfb8aa3b, v54
	v_mul_f32_e32 v57, 0xbfb8aa3b, v55
	v_exp_f32_e32 v56, v56
	v_exp_f32_e32 v57, v57
	v_add_f32_e32 v50, 1.0, v50
	v_add_f32_e32 v51, 1.0, v51
	v_rcp_f32_e32 v50, v50
	v_rcp_f32_e32 v51, v51
	v_add_f32_e32 v56, 1.0, v56
	v_add_f32_e32 v57, 1.0, v57
	v_rcp_f32_e32 v56, v56
	v_rcp_f32_e32 v57, v57
	v_pk_mul_f32 v[52:53], v[60:61], v[0:1] op_sel_hi:[1,0]
	v_pk_mul_f32 v[48:49], v[50:51], v[48:49]
	v_pk_mul_f32 v[50:51], v[62:63], v[0:1] op_sel_hi:[1,0]
	v_pk_mul_f32 v[48:49], v[52:53], v[48:49]
	v_pk_mul_f32 v[52:53], v[56:57], v[54:55]
	v_cvt_pk_bf16_f32 v48, v48, v49
	v_pk_mul_f32 v[50:51], v[50:51], v[52:53]
	v_lshlrev_b32_e32 v52, 16, v83
	v_cvt_pk_bf16_f32 v49, v50, v51
	global_store_dwordx2 v[4:5], v[48:49], off offset:112
	v_lshlrev_b32_e32 v48, 16, v82
	v_mul_f32_e32 v49, 0xbfb8aa3b, v48
	v_exp_f32_e32 v50, v49
	v_and_b32_e32 v49, 0xffff0000, v82
	v_mul_f32_e32 v51, 0xbfb8aa3b, v49
	v_and_b32_e32 v53, 0xffff0000, v83
	v_exp_f32_e32 v51, v51
	v_mul_f32_e32 v54, 0xbfb8aa3b, v52
	v_mul_f32_e32 v55, 0xbfb8aa3b, v53
	v_exp_f32_e32 v54, v54
	v_exp_f32_e32 v55, v55
	v_add_f32_e32 v50, 1.0, v50
	v_add_f32_e32 v51, 1.0, v51
	v_rcp_f32_e32 v50, v50
	v_rcp_f32_e32 v51, v51
	v_add_f32_e32 v54, 1.0, v54
	v_add_f32_e32 v55, 1.0, v55
	v_rcp_f32_e32 v54, v54
	v_rcp_f32_e32 v55, v55
	v_pk_mul_f32 v[48:49], v[50:51], v[48:49]
	s_nop 0
	v_pk_mul_f32 v[32:33], v[32:33], v[48:49]
	v_pk_mul_f32 v[48:49], v[54:55], v[52:53]
	v_cvt_pk_bf16_f32 v32, v32, v33
	v_pk_mul_f32 v[34:35], v[34:35], v[48:49]
; __device__ __forceinline__ float silu_f(float z) { return z * __builtin_amdgcn_rcpf(1.0f + __builtin_amdgcn_exp2f(-LOG2E * z)); }
; __device__ __forceinline__ float bf_lo(unsigned v) { return __uint_as_float(v << 16); }
; __device__ __forceinline__ float bf_hi(unsigned v) { return __uint_as_float(v & 0xffff0000u); }
; template <int MODE>
; __device__ __forceinline__ void attn_unit(const Params& P, LAS unsigned char* lds, const int b, const int h, const int qb) {
;     ...
;     if (FOX) {
; #pragma unroll
;         for (int d = 0; d < 4; ++d)
; #pragma unroll
;             for (int a = 0; a < 4; ++a) { const int d0 = 32 * d + 8 * a + 4 * hh; const u32x2 z2 = zv[d][a];
;                 const float o0 = O[d][4 * a] * inv1 * silu_f(bf_lo(z2.x)), o1 = O[d][4 * a + 1] * inv1 * silu_f(bf_hi(z2.x));
;                 const float o2 = O[d][4 * a + 2] * inv1 * silu_f(bf_lo(z2.y)), o3 = O[d][4 * a + 3] * inv1 * silu_f(bf_hi(z2.y));
;                 u32x2 ov; ov.x = cvt_pk_bf16(o0, o1); ov.y = cvt_pk_bf16(o2, o3); *(u32x2*)(mix + d0) = ov; }
;         __syncthreads();
	v_lshlrev_b32_e32 v48, 16, v81
	v_cvt_pk_bf16_f32 v33, v34, v35
	global_store_dwordx2 v[4:5], v[32:33], off offset:128
	v_lshlrev_b32_e32 v32, 16, v80
	v_mul_f32_e32 v33, 0xbfb8aa3b, v32
	v_exp_f32_e32 v34, v33
	v_and_b32_e32 v33, 0xffff0000, v80
	v_mul_f32_e32 v35, 0xbfb8aa3b, v33
	v_and_b32_e32 v49, 0xffff0000, v81
	v_exp_f32_e32 v35, v35
	v_mul_f32_e32 v50, 0xbfb8aa3b, v48
	v_mul_f32_e32 v51, 0xbfb8aa3b, v49
	v_exp_f32_e32 v50, v50
	v_exp_f32_e32 v51, v51
	v_add_f32_e32 v34, 1.0, v34
	v_add_f32_e32 v35, 1.0, v35
	v_rcp_f32_e32 v34, v34
	v_rcp_f32_e32 v35, v35
	v_add_f32_e32 v50, 1.0, v50
	v_add_f32_e32 v51, 1.0, v51
	v_rcp_f32_e32 v50, v50
	v_rcp_f32_e32 v51, v51
	v_pk_mul_f32 v[32:33], v[34:35], v[32:33]
	v_pk_mul_f32 v[34:35], v[38:39], v[0:1] op_sel_hi:[1,0]
	v_pk_mul_f32 v[32:33], v[36:37], v[32:33]
	v_pk_mul_f32 v[36:37], v[50:51], v[48:49]
	v_cvt_pk_bf16_f32 v32, v32, v33
	v_pk_mul_f32 v[34:35], v[34:35], v[36:37]
	v_and_b32_e32 v37, 0xffff0000, v15
	v_cvt_pk_bf16_f32 v33, v34, v35
	global_store_dwordx2 v[4:5], v[32:33], off offset:144
	v_lshlrev_b32_e32 v32, 16, v14
	v_mul_f32_e32 v33, 0xbfb8aa3b, v32
	v_exp_f32_e32 v34, v33
	v_and_b32_e32 v33, 0xffff0000, v14
	v_mul_f32_e32 v14, 0xbfb8aa3b, v33
	v_exp_f32_e32 v36, v14
	v_add_f32_e32 v14, 1.0, v34
	v_pk_mul_f32 v[34:35], v[40:41], v[0:1] op_sel_hi:[1,0]
	v_rcp_f32_e32 v14, v14
	v_add_f32_e32 v38, 1.0, v36
	v_lshlrev_b32_e32 v36, 16, v15
	v_mul_f32_e32 v15, 0xbfb8aa3b, v36
	v_exp_f32_e32 v39, v15
	v_mul_f32_e32 v15, 0xbfb8aa3b, v37
	v_exp_f32_e32 v40, v15
	v_rcp_f32_e32 v15, v38
	v_add_f32_e32 v38, 1.0, v39
	v_rcp_f32_e32 v38, v38
	v_add_f32_e32 v39, 1.0, v40
	v_rcp_f32_e32 v39, v39
	v_pk_mul_f32 v[14:15], v[14:15], v[32:33]
	v_pk_mul_f32 v[32:33], v[42:43], v[0:1] op_sel_hi:[1,0]
	v_pk_mul_f32 v[14:15], v[34:35], v[14:15]
	v_pk_mul_f32 v[34:35], v[38:39], v[36:37]
	v_cvt_pk_bf16_f32 v14, v14, v15
	v_pk_mul_f32 v[32:33], v[32:33], v[34:35]
	v_and_b32_e32 v35, 0xffff0000, v13
	v_cvt_pk_bf16_f32 v15, v32, v33
	global_store_dwordx2 v[4:5], v[14:15], off offset:160
	v_lshlrev_b32_e32 v14, 16, v12
	v_mul_f32_e32 v15, 0xbfb8aa3b, v14
	v_exp_f32_e32 v32, v15
	v_and_b32_e32 v15, 0xffff0000, v12
	v_mul_f32_e32 v12, 0xbfb8aa3b, v15
	v_exp_f32_e32 v34, v12
	v_add_f32_e32 v12, 1.0, v32
	v_rcp_f32_e32 v12, v12
	v_pk_mul_f32 v[32:33], v[44:45], v[0:1] op_sel_hi:[1,0]
	v_add_f32_e32 v36, 1.0, v34
	v_lshlrev_b32_e32 v34, 16, v13
	v_mul_f32_e32 v13, 0xbfb8aa3b, v34
	v_exp_f32_e32 v37, v13
	v_mul_f32_e32 v13, 0xbfb8aa3b, v35
	v_exp_f32_e32 v38, v13
	v_rcp_f32_e32 v13, v36
	v_add_f32_e32 v36, 1.0, v37
	v_rcp_f32_e32 v36, v36
	v_add_f32_e32 v37, 1.0, v38
	v_rcp_f32_e32 v37, v37
	v_pk_mul_f32 v[12:13], v[12:13], v[14:15]
	v_pk_mul_f32 v[14:15], v[46:47], v[0:1] op_sel_hi:[1,0]
	v_pk_mul_f32 v[12:13], v[32:33], v[12:13]
	v_pk_mul_f32 v[32:33], v[36:37], v[34:35]
	v_cvt_pk_bf16_f32 v12, v12, v13
	v_pk_mul_f32 v[14:15], v[14:15], v[32:33]
	s_nop 0
	v_cvt_pk_bf16_f32 v13, v14, v15
	global_store_dwordx2 v[4:5], v[12:13], off offset:176
	v_lshlrev_b32_e32 v12, 16, v10
	v_mul_f32_e32 v13, 0xbfb8aa3b, v12
	v_exp_f32_e32 v14, v13
	v_and_b32_e32 v13, 0xffff0000, v10
	v_mul_f32_e32 v10, 0xbfb8aa3b, v13
	v_exp_f32_e32 v32, v10
	v_add_f32_e32 v10, 1.0, v14
	v_pk_mul_f32 v[14:15], v[16:17], v[0:1] op_sel_hi:[1,0]
	v_lshlrev_b32_e32 v16, 16, v11
	v_and_b32_e32 v17, 0xffff0000, v11
	v_mul_f32_e32 v11, 0xbfb8aa3b, v16
	v_exp_f32_e32 v33, v11
	v_mul_f32_e32 v11, 0xbfb8aa3b, v17
	v_exp_f32_e32 v34, v11
	v_add_f32_e32 v32, 1.0, v32
	v_rcp_f32_e32 v10, v10
	v_rcp_f32_e32 v11, v32
	v_add_f32_e32 v32, 1.0, v33
	v_add_f32_e32 v33, 1.0, v34
	v_rcp_f32_e32 v32, v32
	v_rcp_f32_e32 v33, v33
	v_pk_mul_f32 v[10:11], v[10:11], v[12:13]
	v_pk_mul_f32 v[12:13], v[18:19], v[0:1] op_sel_hi:[1,0]
	v_pk_mul_f32 v[10:11], v[14:15], v[10:11]
	v_pk_mul_f32 v[14:15], v[32:33], v[16:17]
	v_cvt_pk_bf16_f32 v10, v10, v11
	v_pk_mul_f32 v[12:13], v[12:13], v[14:15]
	v_and_b32_e32 v15, 0xffff0000, v9
	v_cvt_pk_bf16_f32 v11, v12, v13
	global_store_dwordx2 v[4:5], v[10:11], off offset:192
	v_lshlrev_b32_e32 v10, 16, v8
	v_mul_f32_e32 v11, 0xbfb8aa3b, v10
	v_exp_f32_e32 v12, v11
	v_and_b32_e32 v11, 0xffff0000, v8
	v_mul_f32_e32 v8, 0xbfb8aa3b, v11
	v_exp_f32_e32 v14, v8
	v_add_f32_e32 v8, 1.0, v12
	v_rcp_f32_e32 v8, v8
	v_pk_mul_f32 v[12:13], v[20:21], v[0:1] op_sel_hi:[1,0]
	v_add_f32_e32 v16, 1.0, v14
	v_lshlrev_b32_e32 v14, 16, v9
	v_mul_f32_e32 v9, 0xbfb8aa3b, v14
	v_exp_f32_e32 v17, v9
	v_mul_f32_e32 v9, 0xbfb8aa3b, v15
	v_exp_f32_e32 v18, v9
	v_rcp_f32_e32 v9, v16
	v_add_f32_e32 v16, 1.0, v17
	v_rcp_f32_e32 v16, v16
	v_add_f32_e32 v17, 1.0, v18
	v_rcp_f32_e32 v17, v17
	v_pk_mul_f32 v[8:9], v[8:9], v[10:11]
	v_pk_mul_f32 v[10:11], v[22:23], v[0:1] op_sel_hi:[1,0]
	v_pk_mul_f32 v[8:9], v[12:13], v[8:9]
	v_pk_mul_f32 v[12:13], v[16:17], v[14:15]
	v_cvt_pk_bf16_f32 v8, v8, v9
	v_pk_mul_f32 v[10:11], v[10:11], v[12:13]
	v_and_b32_e32 v13, 0xffff0000, v7
	v_cvt_pk_bf16_f32 v9, v10, v11
	global_store_dwordx2 v[4:5], v[8:9], off offset:208
	v_lshlrev_b32_e32 v8, 16, v6
	v_mul_f32_e32 v9, 0xbfb8aa3b, v8
	v_exp_f32_e32 v10, v9
	v_and_b32_e32 v9, 0xffff0000, v6
	v_mul_f32_e32 v6, 0xbfb8aa3b, v9
	v_exp_f32_e32 v12, v6
	v_add_f32_e32 v6, 1.0, v10
	v_rcp_f32_e32 v6, v6
	v_pk_mul_f32 v[10:11], v[24:25], v[0:1] op_sel_hi:[1,0]
	v_add_f32_e32 v14, 1.0, v12
	v_lshlrev_b32_e32 v12, 16, v7
	v_mul_f32_e32 v7, 0xbfb8aa3b, v12
	v_exp_f32_e32 v15, v7
	v_mul_f32_e32 v7, 0xbfb8aa3b, v13
	v_exp_f32_e32 v16, v7
	v_rcp_f32_e32 v7, v14
	v_add_f32_e32 v14, 1.0, v15
	v_rcp_f32_e32 v14, v14
	v_add_f32_e32 v15, 1.0, v16
	v_rcp_f32_e32 v15, v15
	v_pk_mul_f32 v[6:7], v[6:7], v[8:9]
	v_pk_mul_f32 v[8:9], v[26:27], v[0:1] op_sel_hi:[1,0]
	v_pk_mul_f32 v[6:7], v[10:11], v[6:7]
	v_pk_mul_f32 v[10:11], v[14:15], v[12:13]
	v_cvt_pk_bf16_f32 v6, v6, v7
	v_pk_mul_f32 v[8:9], v[8:9], v[10:11]
	v_and_b32_e32 v11, 0xffff0000, v3
	v_cvt_pk_bf16_f32 v7, v8, v9
	global_store_dwordx2 v[4:5], v[6:7], off offset:224
	v_lshlrev_b32_e32 v6, 16, v2
	v_mul_f32_e32 v7, 0xbfb8aa3b, v6
	v_exp_f32_e32 v8, v7
	v_and_b32_e32 v7, 0xffff0000, v2
	v_mul_f32_e32 v2, 0xbfb8aa3b, v7
	v_exp_f32_e32 v10, v2
	v_add_f32_e32 v2, 1.0, v8
	v_rcp_f32_e32 v2, v2
	v_pk_mul_f32 v[8:9], v[28:29], v[0:1] op_sel_hi:[1,0]
	v_add_f32_e32 v12, 1.0, v10
	v_lshlrev_b32_e32 v10, 16, v3
	v_mul_f32_e32 v3, 0xbfb8aa3b, v10
	v_exp_f32_e32 v13, v3
	v_mul_f32_e32 v3, 0xbfb8aa3b, v11
	v_exp_f32_e32 v14, v3
	v_rcp_f32_e32 v3, v12
	v_add_f32_e32 v12, 1.0, v13
	v_rcp_f32_e32 v12, v12
	v_add_f32_e32 v13, 1.0, v14
	v_rcp_f32_e32 v13, v13
	v_pk_mul_f32 v[2:3], v[2:3], v[6:7]
	v_pk_mul_f32 v[6:7], v[30:31], v[0:1] op_sel_hi:[1,0]
	v_pk_mul_f32 v[2:3], v[8:9], v[2:3]
	v_pk_mul_f32 v[8:9], v[12:13], v[10:11]
	v_cvt_pk_bf16_f32 v2, v2, v3
	v_pk_mul_f32 v[6:7], v[6:7], v[8:9]
	s_nop 0
	v_cvt_pk_bf16_f32 v3, v6, v7
	global_store_dwordx2 v[4:5], v[2:3], off offset:240
	s_barrier

; template <int MODE>
; __device__ __forceinline__ void attn_unit(const Params& P, LAS unsigned char* lds, const int b, const int h, const int qb) {
;     ...
;             if constexpr (MODE == 1) {
;                 bf16x8 kf[8];
;                 const unsigned kb_ = (unsigned)(uintptr_t)Kb + kra, c0 = mp * 8 + hh;
;                 k_issue4(kf, kb_ + (((c0) ^ kswz) << 4), kb_ + (((c0 + 2) ^ kswz) << 4), kb_ + (((c0 + 4) ^ kswz) << 4), kb_ + (((c0 + 6) ^ kswz) << 4));
;                 v_issue<0>(va, vaddr);
;                 k_wait<8>(kf);
; #pragma unroll
;                 for (int ks = 0; ks < 4; ++ks) { s[0] = MFMA32(kf[2 * ks], Qf[ks], s[0]); s[1] = MFMA32(kf[2 * ks + 1], Qf[ks], s[1]); }
;                 v_issue<1>(vb, vaddr);
;             } else {
; #pragma unroll
;             for (int ks = 0; ks < NQ; ++ks) {
;                 const unsigned chunk = mp * 8 + 2 * ks + hh;
;                 const unsigned off = kra + ((chunk ^ kswz) << 4);
;                 const bf16x8 a0 = *(const LAS bf16x8*)(Kb + off), a1 = *(const LAS bf16x8*)(Kb + off + 8192);
;                 s[0] = MFMA32(a0, Qf[ks], s[0]); s[1] = MFMA32(a1, Qf[ks], s[1]);
;             }
;             v_issue<0>(va, vaddr);
;             }
;             if (FOX) {
;                 const LAS float* cl = (const LAS float*)(lds + AL_CLS + (cur * 8 + w) * 256) + 8 * hh;
; #pragma unroll
;                 for (int blk = 0; blk < 2; ++blk)
; #pragma unroll
;                     for (int j4 = 0; j4 < 4; ++j4) { const f32x4 c = *(const LAS f32x4*)(cl + 32 * blk + 16 * (j4 >> 1) + 4 * (j4 & 1));
; #pragma unroll
;                         for (int e = 0; e < 4; ++e) s[blk][4 * j4 + e] -= c[e]; }
;             } else if (q0w - kt * 64 - 63 < 128) {
;                 const LAS float* bl = (const LAS float*)(lds + AL_BIAS);
; #pragma unroll
;                 for (int blk = 0; blk < 2; ++blk)
; #pragma unroll
;                     for (int i = 0; i < 16; ++i) { const int dist = q - (kbase + 32 * blk + 16 * (i >> 3) + (i & 7)); const int di = dist < 0 ? 0 : (dist > 128 ? 128 : dist); s[blk][i] += bl[di]; }
;             }
;             if (kt * 64 + 63 > q0w) {
; #pragma unroll
;                 for (int blk = 0; blk < 2; ++blk)
; #pragma unroll
;                     for (int i = 0; i < 16; ++i) { if (kbase + 32 * blk + 16 * (i >> 3) + (i & 7) > q) s[blk][i] = -INFINITY; }
;             }
.Lm1_fast:
	v_mfma_f32_32x32x16_bf16 v[96:111], v[2:5], v[112:115], 0
	v_mfma_f32_32x32x16_bf16 v[96:111], v[10:13], v[116:119], v[96:111]
	v_mfma_f32_32x32x16_bf16 v[96:111], v[168:171], v[120:123], v[96:111]
	v_mfma_f32_32x32x16_bf16 v[96:111], v[180:183], v[124:127], v[96:111]
	ds_read_b64_tr_b16 v[168:169], v0 offset:0x1000
	ds_read_b64_tr_b16 v[170:171], v0 offset:0x1100
	ds_read_b64_tr_b16 v[10:11], v0 offset:0x1200
	ds_read_b64_tr_b16 v[12:13], v0 offset:0x1300
	ds_read_b64_tr_b16 v[180:181], v0 offset:0x1400
	ds_read_b64_tr_b16 v[182:183], v0 offset:0x1500
	ds_read_b64_tr_b16 v[2:3], v0 offset:0x1600
	ds_read_b64_tr_b16 v[4:5], v0 offset:0x1700
	v_mfma_f32_32x32x16_bf16 v[80:95], v[6:9], v[112:115], 0
	s_nop 2
	v_exp_f32_e32 v14, v96
	v_exp_f32_e32 v15, v97
	v_mfma_f32_32x32x16_bf16 v[80:95], v[128:131], v[116:119], v[80:95]
	v_exp_f32_e32 v240, v98
	v_exp_f32_e32 v241, v99
	v_exp_f32_e32 v242, v100
	v_mfma_f32_32x32x16_bf16 v[80:95], v[172:175], v[120:123], v[80:95]
	v_exp_f32_e32 v243, v101
	v_exp_f32_e32 v244, v102
	v_exp_f32_e32 v245, v103
	v_mfma_f32_32x32x16_bf16 v[80:95], v[184:187], v[124:127], v[80:95]
	v_cvt_pk_bf16_f32 v96, v14, v15
	v_cvt_pk_bf16_f32 v97, v240, v241
	v_cvt_pk_bf16_f32 v98, v242, v243
	v_cvt_pk_bf16_f32 v99, v244, v245
	v_exp_f32_e32 v246, v104
	s_waitcnt lgkmcnt(8)
	v_mfma_f32_32x32x16_bf16 v[64:79], v[144:147], v[96:99], v[64:79]
	ds_read_b64_tr_b16 v[6:7], v0 offset:0x2000
	ds_read_b64_tr_b16 v[8:9], v0 offset:0x2100
	ds_read_b64_tr_b16 v[128:129], v0 offset:0x2200
	ds_read_b64_tr_b16 v[130:131], v0 offset:0x2300
	ds_read_b64_tr_b16 v[172:173], v0 offset:0x2400
	ds_read_b64_tr_b16 v[174:175], v0 offset:0x2500
	ds_read_b64_tr_b16 v[184:185], v0 offset:0x2600
	ds_read_b64_tr_b16 v[186:187], v0 offset:0x2700
	v_mfma_f32_32x32x16_bf16 v[48:63], v[140:143], v[96:99], v[48:63]
	v_exp_f32_e32 v247, v105
	v_exp_f32_e32 v248, v106
	v_exp_f32_e32 v249, v107
	v_mfma_f32_32x32x16_bf16 v[32:47], v[136:139], v[96:99], v[32:47]
	v_exp_f32_e32 v250, v108
	v_exp_f32_e32 v251, v109
	v_exp_f32_e32 v252, v110
	v_mfma_f32_32x32x16_bf16 v[16:31], v[132:135], v[96:99], v[16:31]
	v_exp_f32_e32 v236, v111
	v_add_f32_e32 v14, v15, v14
	v_cvt_pk_bf16_f32 v100, v246, v247
	v_cvt_pk_bf16_f32 v101, v248, v249
	v_cvt_pk_bf16_f32 v102, v250, v251
	v_add_f32_e32 v14, v240, v14
	v_cvt_pk_bf16_f32 v103, v252, v236
	v_add_f32_e32 v14, v241, v14
	s_waitcnt lgkmcnt(8)
	v_mfma_f32_32x32x16_bf16 v[64:79], v[168:171], v[100:103], v[64:79]
	ds_read_b64_tr_b16 v[144:145], v0 offset:0x3000
	ds_read_b64_tr_b16 v[146:147], v0 offset:0x3100
	ds_read_b64_tr_b16 v[140:141], v0 offset:0x3200
	ds_read_b64_tr_b16 v[142:143], v0 offset:0x3300
	ds_read_b64_tr_b16 v[136:137], v0 offset:0x3400
	ds_read_b64_tr_b16 v[138:139], v0 offset:0x3500
	ds_read_b64_tr_b16 v[132:133], v0 offset:0x3600
	ds_read_b64_tr_b16 v[134:135], v0 offset:0x3700
	v_mfma_f32_32x32x16_bf16 v[48:63], v[10:13], v[100:103], v[48:63]
	v_exp_f32_e32 v104, v80
	v_exp_f32_e32 v105, v81
	v_exp_f32_e32 v106, v82
	v_mfma_f32_32x32x16_bf16 v[32:47], v[180:183], v[100:103], v[32:47]
	v_exp_f32_e32 v107, v83
	v_exp_f32_e32 v108, v84
	v_exp_f32_e32 v109, v85
	v_mfma_f32_32x32x16_bf16 v[16:31], v[2:5], v[100:103], v[16:31]
	v_exp_f32_e32 v110, v86
	v_exp_f32_e32 v111, v87
	v_cvt_pk_bf16_f32 v80, v104, v105
	v_cvt_pk_bf16_f32 v81, v106, v107
	v_cvt_pk_bf16_f32 v82, v108, v109
	v_add_f32_e32 v14, v242, v14
	v_cvt_pk_bf16_f32 v83, v110, v111
	v_add_f32_e32 v14, v243, v14
	s_waitcnt lgkmcnt(8)
	v_mfma_f32_32x32x16_bf16 v[64:79], v[6:9], v[80:83], v[64:79]
	v_exp_f32_e32 v2, v88
	v_exp_f32_e32 v3, v89
	v_exp_f32_e32 v4, v90
	v_mfma_f32_32x32x16_bf16 v[48:63], v[128:131], v[80:83], v[48:63]
	v_exp_f32_e32 v5, v91
	v_exp_f32_e32 v10, v92
	v_exp_f32_e32 v11, v93
	v_mfma_f32_32x32x16_bf16 v[32:47], v[172:175], v[80:83], v[32:47]
	v_exp_f32_e32 v12, v94
	v_exp_f32_e32 v13, v95
	v_add_f32_e32 v14, v244, v14
	v_add_f32_e32 v14, v245, v14
	v_mfma_f32_32x32x16_bf16 v[16:31], v[184:187], v[80:83], v[16:31]
	v_cvt_pk_bf16_f32 v84, v2, v3
	v_cvt_pk_bf16_f32 v85, v4, v5
	v_cvt_pk_bf16_f32 v86, v10, v11
	v_add_f32_e32 v14, v246, v14
	v_cvt_pk_bf16_f32 v87, v12, v13
	v_add_f32_e32 v14, v247, v14
	v_add_f32_e32 v14, v248, v14
	s_waitcnt lgkmcnt(0)
	v_add_f32_e32 v14, v249, v14
	v_add_f32_e32 v14, v250, v14
	v_add_f32_e32 v14, v251, v14
	v_add_f32_e32 v14, v252, v14
	v_add_f32_e32 v14, v236, v14
	s_add_i32 s41, s40, 3
	s_cmp_ge_u32 s41, s22
	s_cbranch_scc1 .Lm1f_nodma
	s_cmpk_gt_u32 s58, 0xff
	s_cbranch_scc1 .Lm1f_nodma
	v_mfma_f32_32x32x16_bf16 v[64:79], v[144:147], v[84:87], v[64:79]
	s_mov_b64 s[70:71], 0x1000
	s_add_i32 s41, s38, 0x18000
	s_and_b32 s41, s41, 0x18000
	s_add_i32 s41, s77, s41
	v_lshl_add_u64 v[240:241], v[152:153], 0, s[68:69]
	v_lshl_add_u64 v[242:243], v[240:241], 0, s[42:43]
	s_mov_b32 m0, s41
	v_lshl_add_u64 v[240:241], v[240:241], 0, s[44:45]
	global_load_lds_dwordx4 v[242:243], off
	v_mfma_f32_32x32x16_bf16 v[48:63], v[140:143], v[84:87], v[48:63]
	s_add_i32 m0, s41, 0x1000
	v_lshl_add_u64 v[242:243], v[242:243], 0, s[70:71]
	global_load_lds_dwordx4 v[242:243], off
	s_add_i32 m0, s41, 0x2000
	v_lshl_add_u64 v[242:243], v[240:241], 0, s[70:71]
	global_load_lds_dwordx4 v[240:241], off
	s_add_i32 m0, s41, 0x3000
	v_lshl_add_u64 v[240:241], v[154:155], 0, s[68:69]
	global_load_lds_dwordx4 v[242:243], off
	v_add_f32_e32 v14, v104, v14
	v_add_f32_e32 v14, v105, v14
	v_add_f32_e32 v14, v106, v14
	v_add_f32_e32 v14, v107, v14
	v_mfma_f32_32x32x16_bf16 v[32:47], v[136:139], v[84:87], v[32:47]
	v_lshl_add_u64 v[242:243], v[240:241], 0, s[48:49]
	s_add_i32 m0, s41, 0x4000
	v_lshl_add_u64 v[240:241], v[240:241], 0, s[50:51]
	global_load_lds_dwordx4 v[242:243], off
	s_add_i32 m0, s41, 0x5000
	v_lshl_add_u64 v[242:243], v[242:243], 0, s[70:71]
	global_load_lds_dwordx4 v[242:243], off
	v_add_f32_e32 v14, v108, v14
	v_add_f32_e32 v14, v109, v14
	v_add_f32_e32 v14, v110, v14
	v_add_f32_e32 v14, v111, v14
	v_add_f32_e32 v14, v2, v14
	v_add_f32_e32 v14, v3, v14
	v_mfma_f32_32x32x16_bf16 v[16:31], v[132:135], v[84:87], v[16:31]
	s_add_i32 m0, s41, 0x6000
	v_lshl_add_u64 v[242:243], v[240:241], 0, s[70:71]
	global_load_lds_dwordx4 v[240:241], off
	s_add_i32 m0, s41, 0x7000
	s_nop 0
	global_load_lds_dwordx4 v[242:243], off
	v_add_f32_e32 v14, v4, v14
	v_add_f32_e32 v14, v5, v14
	v_add_f32_e32 v14, v10, v14
	v_add_f32_e32 v14, v11, v14
	v_add_f32_e32 v14, v12, v14
	v_add_f32_e32 v14, v13, v14
	v_add_f32_e32 v163, v163, v14
	s_branch .LBB0_474

; template <int MODE>
; __device__ __forceinline__ void attn_unit(const Params& P, LAS unsigned char* lds, const int b, const int h, const int qb) {
;     ...
;     bf16_t* mix = (bf16_t*)(P.ws + WS_MIX) + (tokbase + q) * DM + colO;
;     const bf16_t* zp = Zb + (size_t)q * RS;
;     const float inv1 = 1.0f / (l1 + __shfl_xor(l1, 32));
;     u32x2 zv[4][4]; f32x4 gv[4][4];
;     if (FOX || mp == 0) {
; #pragma unroll
;         for (int d = 0; d < 4; ++d)
; #pragma unroll
;             for (int a = 0; a < 4; ++a) { const int d0 = 32 * d + 8 * a + 4 * hh; zv[d][a] = *(const u32x2*)(zp + d0); if (!FOX) gv[d][a] = *(const f32x4*)(P.in[I_DON] + d0); }
;     }
.LBB0_490:
	s_and_saveexec_b64 s[68:69], s[4:5]
	s_cbranch_execz .Lqp_m1
	s_and_b32 vcc_lo, s3, 7
	s_lshl_b32 vcc_lo, vcc_lo, 2
	v_mov_b32_e32 v0, vcc_lo
	v_mov_b32_e32 v2, 1
	global_atomic_add v253, v0, v2, s[52:53] sc0
.Lqp_m1:
	s_or_b64 exec, exec, s[68:69]
	v_and_b32_e32 v2, 64, v179
	v_xor_b32_e32 v0, 32, v179
	v_add_u32_e32 v2, 64, v2
	v_cmp_lt_i32_e32 vcc, v0, v2
	s_cmpk_lt_u32 s58, 0x100
	s_cselect_b64 s[68:69], -1, 0
	v_cndmask_b32_e32 v0, v179, v0, vcc
	v_lshlrev_b32_e32 v228, 2, v0
	ds_bpermute_b32 v164, v228, v163
	s_cmpk_gt_u32 s58, 0xff
	s_cbranch_scc1 .LBB0_492
	s_add_u32 s22, s92, s66
	s_addc_u32 s23, s93, s67
	v_lshlrev_b32_e32 v0, 1, v149
	v_lshl_add_u64 v[2:3], s[22:23], 0, v[0:1]
	v_mov_b32_e32 v149, v1
	v_lshl_add_u64 v[2:3], v[2:3], 0, v[148:149]
	global_load_dwordx4 v[128:131], v150, s[46:47]
	global_load_dwordx4 v[124:127], v150, s[46:47] offset:32
	global_load_dwordx2 v[160:161], v[2:3], off
	global_load_dwordx2 v[170:171], v[2:3], off offset:16
	global_load_dwordx2 v[168:169], v[2:3], off offset:32
	global_load_dwordx2 v[158:159], v[2:3], off offset:48
	global_load_dwordx4 v[120:123], v150, s[46:47] offset:64
	global_load_dwordx4 v[116:119], v150, s[46:47] offset:96
	global_load_dwordx4 v[112:115], v150, s[46:47] offset:128
	global_load_dwordx4 v[108:111], v150, s[46:47] offset:160
	global_load_dwordx2 v[156:157], v[2:3], off offset:64
	global_load_dwordx2 v[154:155], v[2:3], off offset:80
	global_load_dwordx2 v[152:153], v[2:3], off offset:96
	global_load_dwordx2 v[146:147], v[2:3], off offset:112
	global_load_dwordx4 v[104:107], v150, s[46:47] offset:192
	global_load_dwordx4 v[100:103], v150, s[46:47] offset:224
	global_load_dwordx4 v[96:99], v150, s[46:47] offset:256
	global_load_dwordx4 v[92:95], v150, s[46:47] offset:288
	global_load_dwordx2 v[144:145], v[2:3], off offset:128
	global_load_dwordx2 v[142:143], v[2:3], off offset:144
	global_load_dwordx2 v[140:141], v[2:3], off offset:160
	global_load_dwordx2 v[138:139], v[2:3], off offset:176
	global_load_dwordx4 v[88:91], v150, s[46:47] offset:320
	global_load_dwordx4 v[84:87], v150, s[46:47] offset:352
	global_load_dwordx4 v[80:83], v150, s[46:47] offset:384
	global_load_dwordx4 v[10:13], v150, s[46:47] offset:416
	global_load_dwordx2 v[136:137], v[2:3], off offset:192
	global_load_dwordx2 v[134:135], v[2:3], off offset:208
	global_load_dwordx2 v[132:133], v[2:3], off offset:224
	global_load_dwordx2 v[14:15], v[2:3], off offset:240
	global_load_dwordx4 v[6:9], v150, s[46:47] offset:448
	s_nop 0
	global_load_dwordx4 v[2:5], v150, s[46:47] offset:480

; template <int MODE>
; __device__ __forceinline__ void attn_unit(const Params& P, LAS unsigned char* lds, const int b, const int h, const int qb) {
;     ...
;     bf16_t* mix = (bf16_t*)(P.ws + WS_MIX) + (tokbase + q) * DM + colO;
;     const bf16_t* zp = Zb + (size_t)q * RS;
;     const float inv1 = 1.0f / (l1 + __shfl_xor(l1, 32));
;     u32x2 zv[4][4]; f32x4 gv[4][4];
;     if (FOX || mp == 0) {
; #pragma unroll
;         for (int d = 0; d < 4; ++d)
; #pragma unroll
;             for (int a = 0; a < 4; ++a) { const int d0 = 32 * d + 8 * a + 4 * hh; zv[d][a] = *(const u32x2*)(zp + d0); if (!FOX) gv[d][a] = *(const f32x4*)(P.in[I_DON] + d0); }
;     }
.LBB0_522:
	s_and_saveexec_b64 s[64:65], s[4:5]
	s_cbranch_execz .Lqp_m2
	s_and_b32 vcc_lo, s3, 7
	s_lshl_b32 vcc_lo, vcc_lo, 2
	v_mov_b32_e32 v0, vcc_lo
	v_mov_b32_e32 v2, 1
	global_atomic_add v253, v0, v2, s[52:53] sc0
.Lqp_m2:
	s_or_b64 exec, exec, s[64:65]
	v_and_b32_e32 v2, 64, v179
	v_xor_b32_e32 v0, 32, v179
	v_add_u32_e32 v2, 64, v2
	v_cmp_lt_i32_e32 vcc, v0, v2
	s_cmpk_lt_u32 s0, 0x100
	s_cselect_b64 s[64:65], -1, 0
	v_cndmask_b32_e32 v0, v179, v0, vcc
	v_lshlrev_b32_e32 v236, 2, v0
	ds_bpermute_b32 v168, v236, v164
	s_cmpk_gt_u32 s0, 0xff
	s_cbranch_scc1 .LBB0_524
	s_add_u32 s0, s92, s8
	s_addc_u32 s1, s93, s9
	v_lshlrev_b32_e32 v0, 1, v133
	v_lshl_add_u64 v[2:3], s[0:1], 0, v[0:1]
	v_mov_b32_e32 v133, v1
	v_lshl_add_u64 v[2:3], v[2:3], 0, v[132:133]
	global_load_dwordx4 v[128:131], v134, s[46:47]
	global_load_dwordx4 v[124:127], v134, s[46:47] offset:32
	global_load_dwordx2 v[166:167], v[2:3], off
	global_load_dwordx2 v[162:163], v[2:3], off offset:16
	global_load_dwordx2 v[160:161], v[2:3], off offset:32
	global_load_dwordx2 v[158:159], v[2:3], off offset:48
	global_load_dwordx4 v[120:123], v134, s[46:47] offset:64
	global_load_dwordx4 v[116:119], v134, s[46:47] offset:96
	global_load_dwordx4 v[112:115], v134, s[46:47] offset:128
	global_load_dwordx4 v[108:111], v134, s[46:47] offset:160
	global_load_dwordx2 v[156:157], v[2:3], off offset:64
	global_load_dwordx2 v[154:155], v[2:3], off offset:80
	global_load_dwordx2 v[152:153], v[2:3], off offset:96
	global_load_dwordx2 v[150:151], v[2:3], off offset:112
	global_load_dwordx4 v[104:107], v134, s[46:47] offset:192
	global_load_dwordx4 v[100:103], v134, s[46:47] offset:224
	global_load_dwordx4 v[96:99], v134, s[46:47] offset:256
	global_load_dwordx4 v[92:95], v134, s[46:47] offset:288
	global_load_dwordx2 v[148:149], v[2:3], off offset:128
	global_load_dwordx2 v[146:147], v[2:3], off offset:144
	global_load_dwordx2 v[144:145], v[2:3], off offset:160
	global_load_dwordx2 v[142:143], v[2:3], off offset:176
	global_load_dwordx4 v[88:91], v134, s[46:47] offset:320
	global_load_dwordx4 v[84:87], v134, s[46:47] offset:352
	global_load_dwordx4 v[80:83], v134, s[46:47] offset:384
	global_load_dwordx4 v[10:13], v134, s[46:47] offset:416
	global_load_dwordx2 v[140:141], v[2:3], off offset:192
	global_load_dwordx2 v[138:139], v[2:3], off offset:208
	global_load_dwordx2 v[136:137], v[2:3], off offset:224
	global_load_dwordx2 v[14:15], v[2:3], off offset:240
	global_load_dwordx4 v[6:9], v134, s[46:47] offset:448
	s_nop 0
	global_load_dwordx4 v[2:5], v134, s[46:47] offset:480
